# SSM Y phase and GLU items: weight-fragment loads kept in flight across the first barrier; HL rebuild loop (64-row items) issues its 8 loads together
# baseline (speedup 1.0000x reference)
; template <int K> __device__ __forceinline__ void wave_bfrags(const bf16* Bt, int kb, bf16x8v (&bfr)[8][2], int lane) {
;     const int fr = lane & 15, fq = lane >> 4;
; #pragma unroll
;     for (int ks = 0; ks < 8; ++ks)
; #pragma unroll
;         for (int n = 0; n < 2; ++n) bfr[ks][n] = *(const bf16x8v*)(Bt + (size_t)(n * 16 + fr) * K + kb * 256 + ks * 32 + 8 * fq);
; }
; template <int PH, int MT> __device__ __forceinline__ void ssm_gemm_rows(Frame& F, const Args& AR, int l, int g, int row0) {
;     ...
;     bf16x8v b0[8][2];
;     wave_bfrags<K>(Bt, 0, b0, F.lane);
;     __syncthreads();
;     if (F.tid < 128) { const int dir = F.tid >> 6, p = F.tid & 63, t = row0 >> 6, b = t >> 2, i = t & 3;
;         const float* ET = (const float*)(F.ws + WS_ET) + (size_t)g * 256 + dir * 128 + p;
;         const f32x2 a64 = *(const f32x2*)(POW + ((((size_t)(l * 2 + dir) * 32 + g) * 65 + 64) * 64 + p) * 2);
;         float hr = ET[(size_t)(8 + b) * 8192], hi = ET[(size_t)(8 + b) * 8192 + 64];
;         if (dir == 0) { for (int j = 0; j < i; ++j) { const float er = ET[(size_t)(4 * b + j) * 8192], ei = ET[(size_t)(4 * b + j) * 8192 + 64];
;                 const float nr = a64.x * hr - a64.y * hi + er, ni = a64.x * hi + a64.y * hr + ei; hr = nr; hi = ni; } }
;         else { for (int j = 3; j > i; --j) { const float er = ET[(size_t)(4 * b + j) * 8192], ei = ET[(size_t)(4 * b + j) * 8192 + 64];
;                 const float nr = a64.x * hr - a64.y * hi + er, ni = a64.x * hi + a64.y * hr + ei; hr = nr; hi = ni; } }
;         hs[F.tid * 2] = hr; hs[F.tid * 2 + 1] = hi; }
.LBB0_1582:
	s_and_b32 s16, s15, 31
	s_ashr_i32 s17, s15, 5
	s_mov_b64 s[0:1], -1
	s_cmp_gt_i32 s17, 6
	v_lshlrev_b32_e32 v178, 1, v130
	v_lshlrev_b32_e32 v176, 1, v132
	s_cbranch_scc0 .LBB0_1595
	v_readlane_b32 s4, v250, 58
	s_lshl_b32 s0, s16, 18
	v_readlane_b32 s5, v250, 59
	s_mov_b32 s1, s5
	s_or_b32 s0, s0, s10
	v_lshl_add_u64 v[70:71], v[168:169], 0, s[0:1]
	v_mov_b32_e32 v179, v195
	v_mov_b32_e32 v177, v195
	v_lshl_add_u64 v[180:181], v[70:71], 0, v[178:179]
	v_lshl_add_u64 v[6:7], v[70:71], 0, v[176:177]
	global_load_dwordx4 v[106:109], v[180:181], off
	global_load_dwordx4 v[82:85], v[180:181], off offset:64
	global_load_dwordx4 v[110:113], v[6:7], off
	global_load_dwordx4 v[86:89], v[6:7], off offset:64
	global_load_dwordx4 v[74:77], v[180:181], off offset:128
	global_load_dwordx4 v[50:53], v[180:181], off offset:192
	global_load_dwordx4 v[78:81], v[6:7], off offset:128
	global_load_dwordx4 v[54:57], v[6:7], off offset:192
	global_load_dwordx4 v[42:45], v[180:181], off offset:256
	global_load_dwordx4 v[26:29], v[180:181], off offset:320
	global_load_dwordx4 v[46:49], v[6:7], off offset:256
	global_load_dwordx4 v[30:33], v[6:7], off offset:320
	global_load_dwordx4 v[10:13], v[180:181], off offset:384
	global_load_dwordx4 v[2:5], v[180:181], off offset:448
	global_load_dwordx4 v[14:17], v[6:7], off offset:384
	s_nop 0
	global_load_dwordx4 v[6:9], v[6:7], off offset:448
	s_mov_b32 s9, s5
	s_barrier
	s_and_saveexec_b64 s[0:1], s[40:41]
	s_cbranch_execz .LBB0_1587
	s_mov_b32 s5, s9
	s_lshl_b32 s4, s16, 10
	v_lshl_add_u64 v[20:21], v[134:135], 0, s[4:5]
	v_add_co_u32_e32 v22, vcc, 0x48000, v20
	s_nop 1
	v_addc_co_u32_e32 v23, vcc, 0, v21, vcc
	global_load_dword v18, v[22:23], off
	global_load_dword v19, v[22:23], off offset:256
	s_and_saveexec_b64 s[4:5], s[42:43]
	s_cbranch_execz .LBB0_1586
	s_or_b32 s6, s16, s11
	s_mulk_i32 s6, 0x1040
	v_add_lshl_u32 v24, s6, v133, 3
	v_add_co_u32_e32 v22, vcc, 0x20000, v20
	s_nop 1
	v_addc_co_u32_e32 v23, vcc, 0, v21, vcc
	global_load_dwordx2 v[24:25], v24, s[34:35]
	s_nop 0
	global_load_dword v34, v[22:23], off
	global_load_dword v35, v[22:23], off offset:256
	v_add_co_u32_e32 v22, vcc, 0x28000, v20
	s_nop 1
	v_addc_co_u32_e32 v23, vcc, 0, v21, vcc
	global_load_dword v38, v[22:23], off
	global_load_dword v39, v[22:23], off offset:256
	v_add_co_u32_e32 v20, vcc, 0x30000, v20
	s_nop 1
	v_addc_co_u32_e32 v21, vcc, 0, v21, vcc
	global_load_dword v22, v[20:21], off
	global_load_dword v23, v[20:21], off offset:256
	s_waitcnt vmcnt(7)
	v_mov_b32_e32 v20, v19
	s_waitcnt vmcnt(6)
	v_pk_mul_f32 v[20:21], v[20:21], v[24:25] op_sel:[0,1] op_sel_hi:[0,0]
	v_pk_fma_f32 v[36:37], v[18:19], v[24:25], v[20:21] neg_lo:[0,0,1] neg_hi:[0,0,1]
	v_pk_fma_f32 v[18:19], v[18:19], v[24:25], v[20:21] op_sel_hi:[0,1,1]
	v_mov_b32_e32 v37, v19
	s_waitcnt vmcnt(4)
	v_pk_add_f32 v[18:19], v[34:35], v[36:37]
	s_nop 0
	v_pk_mul_f32 v[20:21], v[24:25], v[18:19]
	v_pk_mul_f32 v[18:19], v[24:25], v[18:19] op_sel:[0,1] op_sel_hi:[1,0]
	v_sub_f32_e32 v20, v20, v21
	v_add_f32_e32 v19, v18, v19
	s_waitcnt vmcnt(3)
	v_add_f32_e32 v18, v38, v20
	s_waitcnt vmcnt(2)
	v_add_f32_e32 v20, v39, v19
	v_pk_mul_f32 v[20:21], v[24:25], v[20:21] op_sel:[1,0] op_sel_hi:[0,0]
	v_pk_fma_f32 v[34:35], v[24:25], v[18:19], v[20:21] neg_lo:[0,0,1] neg_hi:[0,0,1]
	v_pk_fma_f32 v[18:19], v[24:25], v[18:19], v[20:21] op_sel_hi:[1,0,1]
	s_nop 0
	v_mov_b32_e32 v35, v19
	s_waitcnt vmcnt(0)
	v_pk_add_f32 v[18:19], v[22:23], v[34:35]

; #define LAS __attribute__((address_space(3)))
; template <int PH, int MT> __device__ __forceinline__ void ssm_gemm_rows(Frame& F, const Args& AR, int l, int g, int row0) {
;     ...
;     for (int idx = F.tid; idx < NROW * 32; idx += NTHR) { const int piece = idx & 1, tok = (idx >> 1) & 15, row = idx >> 5, cr = row0 + row;
;         v4u v = {0u, 0u, 0u, 0u}; if (cr < NCR) v = *(const v4u*)(P + (size_t)(cr * 16 + tok) * DIN + SSM_OFF + g * 16 + piece * 8);
;         *(LAS v4u*)(at + row * LDA + (tok * 16 + piece * 8) * 2) = v; }
;     __syncthreads();
;     { const float* HL = (const float*)(F.ws + WS_SSMS);
;         for (int idx = F.tid; idx < NROW * 16; idx += NTHR) { const int oct = idx & 7, dir = (idx >> 3) & 1, row = idx >> 4, cr = row0 + row;
;             const float* hl = HL + ((size_t)cr * 32 + g) * 256 + dir * 128 + oct * 8;
.LBB0_1590:
	s_or_b64 exec, exec, s[0:1]
	s_mov_b32 s23, s9
	s_waitcnt vmcnt(0) lgkmcnt(0)
	s_barrier
	s_and_saveexec_b64 s[0:1], s[48:49]
	s_cbranch_execz .LBB0_1596
	s_lshl_b32 s4, s16, 10
	v_readlane_b32 s5, v253, 5
	s_add_u32 s4, s5, s4
	v_readlane_b32 s5, v253, 6
	s_addc_u32 s5, s5, 0
	s_or_b32 s18, s16, s11
	s_mov_b64 s[6:7], 0
	v_mov_b32_e32 v92, v137
	v_mov_b32_e32 v93, v131
	s_branch .LBB0_1593

; template <int PH, int MT> __device__ __forceinline__ void ssm_gemm_rows(Frame& F, const Args& AR, int l, int g, int row0) {
;     ...
;     bf16x8v b0[8][2];
;     wave_bfrags<K>(Bt, 0, b0, F.lane);
;     __syncthreads();
;     if (F.tid < 128) { const int dir = F.tid >> 6, p = F.tid & 63, t = row0 >> 6, b = t >> 2, i = t & 3;
;         const float* ET = (const float*)(F.ws + WS_ET) + (size_t)g * 256 + dir * 128 + p;
;         const f32x2 a64 = *(const f32x2*)(POW + ((((size_t)(l * 2 + dir) * 32 + g) * 65 + 64) * 64 + p) * 2);
;         float hr = ET[(size_t)(8 + b) * 8192], hi = ET[(size_t)(8 + b) * 8192 + 64];
;         if (dir == 0) { for (int j = 0; j < i; ++j) { const float er = ET[(size_t)(4 * b + j) * 8192], ei = ET[(size_t)(4 * b + j) * 8192 + 64];
;                 const float nr = a64.x * hr - a64.y * hi + er, ni = a64.x * hi + a64.y * hr + ei; hr = nr; hi = ni; } }
;         else { for (int j = 3; j > i; --j) { const float er = ET[(size_t)(4 * b + j) * 8192], ei = ET[(size_t)(4 * b + j) * 8192 + 64];
.LBB0_1597:
	v_readlane_b32 s4, v250, 58
	s_lshl_b32 s0, s16, 18
	v_readlane_b32 s5, v250, 59
	s_mov_b32 s1, s5
	s_or_b32 s0, s0, s10
	v_lshl_add_u64 v[68:69], v[168:169], 0, s[0:1]
	v_mov_b32_e32 v179, v195
	v_mov_b32_e32 v177, v195
	v_lshl_add_u64 v[66:67], v[68:69], 0, v[178:179]
	v_lshl_add_u64 v[6:7], v[68:69], 0, v[176:177]
	global_load_dwordx4 v[58:61], v[66:67], off
	global_load_dwordx4 v[50:53], v[66:67], off offset:64
	global_load_dwordx4 v[62:65], v[6:7], off
	global_load_dwordx4 v[54:57], v[6:7], off offset:64
	global_load_dwordx4 v[42:45], v[66:67], off offset:128
	global_load_dwordx4 v[34:37], v[66:67], off offset:192
	global_load_dwordx4 v[46:49], v[6:7], off offset:128
	global_load_dwordx4 v[38:41], v[6:7], off offset:192
	global_load_dwordx4 v[26:29], v[66:67], off offset:256
	global_load_dwordx4 v[18:21], v[66:67], off offset:320
	global_load_dwordx4 v[30:33], v[6:7], off offset:256
	global_load_dwordx4 v[22:25], v[6:7], off offset:320
	global_load_dwordx4 v[10:13], v[66:67], off offset:384
	global_load_dwordx4 v[2:5], v[66:67], off offset:448
	global_load_dwordx4 v[14:17], v[6:7], off offset:384
	s_nop 0
	global_load_dwordx4 v[6:9], v[6:7], off offset:448
	s_mov_b32 s21, s5
	s_barrier
	s_and_saveexec_b64 s[0:1], s[40:41]
	s_cbranch_execz .LBB0_1608
	s_lshl_b32 s6, s16, 10
	s_mov_b32 s7, s21
	v_or_b32_e32 v72, s16, v164
	s_movk_i32 s5, 0x1040
	s_ashr_i32 s4, s15, 7
	v_lshl_add_u64 v[70:71], v[162:163], 0, s[6:7]
	v_mad_u64_u32 v[72:73], s[6:7], v72, s5, v[166:167]
	v_mad_i32_i24 v73, v165, s5, v73
	s_ashr_i32 s5, s4, 31
	s_lshl_b64 s[6:7], s[4:5], 15
	v_lshl_add_u64 v[70:71], v[70:71], 0, s[6:7]
	s_mov_b64 s[6:7], 0x40000
	v_lshl_add_u64 v[72:73], v[72:73], 3, s[34:35]
	v_lshl_add_u64 v[74:75], v[70:71], 0, s[6:7]
	v_add_co_u32_e32 v70, vcc, 0x40000, v70
	s_and_b32 s5, s14, 31
	s_nop 0
	v_addc_co_u32_e32 v71, vcc, 0, v71, vcc
	global_load_dwordx2 v[72:73], v[72:73], off
	s_nop 0
	global_load_dword v70, v[70:71], off
	s_nop 0
	global_load_dword v74, v[74:75], off offset:256
	s_lshl_b32 s20, s5, 10
	s_bfe_u32 s5, s15, 0x20005
	s_and_saveexec_b64 s[6:7], s[44:45]
	s_xor_b64 s[6:7], exec, s[6:7]
	s_cbranch_execz .LBB0_1603
	s_cmp_eq_u32 s5, 3
	s_cbranch_scc1 .LBB0_1602
	s_lshl_b32 s8, s4, 2
	s_ashr_i32 s9, s8, 31
	s_lshl_b64 s[8:9], s[8:9], 15
	s_or_b64 s[8:9], s[8:9], s[20:21]
	s_waitcnt vmcnt(2)
	v_pk_mov_b32 v[76:77], v[72:73], v[72:73] op_sel:[1,0]
	v_lshl_add_u64 v[78:79], v[170:171], 0, s[8:9]
	s_mov_b32 s8, 3

; #define LAS __attribute__((address_space(3)))
; __device__ __forceinline__ unsigned pk2(float lo, float hi) { const f32x2cv v = {lo, hi}; return __builtin_bit_cast(unsigned, __builtin_convertvector(v, bf16x2cv)); }
; template <int PH, int MT> __device__ __forceinline__ void ssm_gemm_rows(Frame& F, const Args& AR, int l, int g, int row0) {
;     ...
;     __syncthreads();
;     { const float* HL = (const float*)(F.ws + WS_SSMS);
;         for (int idx = F.tid; idx < NROW * 16; idx += NTHR) { const int oct = idx & 7, dir = (idx >> 3) & 1, row = idx >> 4, cr = row0 + row;
;             const float* hl = HL + ((size_t)cr * 32 + g) * 256 + dir * 128 + oct * 8;
;             f32x4 r0 = *(const f32x4*)hl, r1 = *(const f32x4*)(hl + 4), i0 = *(const f32x4*)(hl + 64), i1 = *(const f32x4*)(hl + 68);
;             if (row < 64) { const int e = dir ? 63 - row : row;
;                 const float* pw = POW + ((((size_t)(l * 2 + dir) * 32 + g) * 65 + e) * 64 + oct * 8) * 2;
;                 const f32x4 w0 = *(const f32x4*)pw, w1 = *(const f32x4*)(pw + 4), w2 = *(const f32x4*)(pw + 8), w3 = *(const f32x4*)(pw + 12);
;                 const LAS float* hp = hs + (dir * 64 + oct * 8) * 2;
;                 const f32x4 h0 = *(const LAS f32x4*)hp, h1 = *(const LAS f32x4*)(hp + 4), h2 = *(const LAS f32x4*)(hp + 8), h3 = *(const LAS f32x4*)(hp + 12);
;                 r0.x += w0.x * h0.x - w0.y * h0.y; i0.x += w0.x * h0.y + w0.y * h0.x;  r0.y += w0.z * h0.z - w0.w * h0.w; i0.y += w0.z * h0.w + w0.w * h0.z;
;                 r0.z += w1.x * h1.x - w1.y * h1.y; i0.z += w1.x * h1.y + w1.y * h1.x;  r0.w += w1.z * h1.z - w1.w * h1.w; i0.w += w1.z * h1.w + w1.w * h1.z;
;                 r1.x += w2.x * h2.x - w2.y * h2.y; i1.x += w2.x * h2.y + w2.y * h2.x;  r1.y += w2.z * h2.z - w2.w * h2.w; i1.y += w2.z * h2.w + w2.w * h2.z;
;                 r1.z += w3.x * h3.x - w3.y * h3.y; i1.z += w3.x * h3.y + w3.y * h3.x;  r1.w += w3.z * h3.z - w3.w * h3.w; i1.w += w3.z * h3.w + w3.w * h3.z; }
;             v4u vr, vi; vr.x = pk2(r0.x, r0.y); vr.y = pk2(r0.z, r0.w); vr.z = pk2(r1.x, r1.y); vr.w = pk2(r1.z, r1.w);
;             vi.x = pk2(i0.x, i0.y); vi.y = pk2(i0.z, i0.w); vi.z = pk2(i1.x, i1.y); vi.w = pk2(i1.z, i1.w);
;             *(LAS v4u*)(at + row * LDA + 512 + (dir * 128 + oct * 8) * 2) = vr; *(LAS v4u*)(at + row * LDA + 512 + (dir * 128 + 64 + oct * 8) * 2) = vi; } }
.LBB0_1611:
	s_or_b64 exec, exec, s[0:1]
	s_mov_b32 s19, s21
	s_waitcnt vmcnt(0) lgkmcnt(0)
	s_barrier
	s_and_saveexec_b64 s[0:1], s[52:53]
	s_cbranch_execz .LBB0_1580
	s_lshl_b32 s4, s16, 10
	v_readlane_b32 s5, v253, 5
	s_add_u32 s4, s5, s4
	v_readlane_b32 s5, v253, 6
	s_addc_u32 s5, s5, 0
	s_or_b32 s9, s16, s11
	s_mov_b64 s[6:7], 0
	v_mov_b32_e32 v70, v137
	v_mov_b32_e32 v71, v131
.LBB0_1613:
	v_bfe_u32 v122, v71, 3, 1
	v_ashrrev_i32_e32 v123, 4, v71
	v_cmp_eq_u32_e32 vcc, 0, v122
	v_sub_u32_e32 v82, 63, v123
	v_add_u32_e32 v72, s8, v123
	v_lshl_or_b32 v80, v122, 5, s9
	v_cndmask_b32_e32 v82, v82, v123, vcc
	v_ashrrev_i32_e32 v73, 31, v72
	v_lshl_add_u32 v80, v80, 6, v80
	v_mov_b32_e32 v81, v195
	v_ashrrev_i32_e32 v83, 31, v82
	v_lshlrev_b64 v[72:73], 15, v[72:73]
	v_lshl_add_u64 v[80:81], v[80:81], 0, v[82:83]
	v_and_b32_e32 v124, 56, v70
	v_lshl_add_u64 v[72:73], s[4:5], 0, v[72:73]
	v_lshlrev_b32_e32 v194, 9, v122
	v_lshlrev_b64 v[80:81], 9, v[80:81]
	v_lshl_add_u64 v[72:73], v[72:73], 0, v[194:195]
	v_lshlrev_b32_e32 v74, 2, v124
	v_mov_b32_e32 v75, v195
	v_lshl_add_u64 v[80:81], s[34:35], 0, v[80:81]
	v_lshlrev_b32_e32 v96, 3, v124
	v_mov_b32_e32 v97, v195
	v_lshl_add_u64 v[112:113], v[72:73], 0, v[74:75]
	v_lshl_add_u64 v[92:93], v[80:81], 0, v[96:97]
	global_load_dwordx4 v[72:75], v[112:113], off offset:256
	global_load_dwordx4 v[76:79], v[112:113], off offset:272
	global_load_dwordx4 v[80:83], v[92:93], off offset:16
	global_load_dwordx4 v[84:87], v[92:93], off
	global_load_dwordx4 v[88:91], v[92:93], off offset:48
	s_nop 0
	global_load_dwordx4 v[92:95], v[92:93], off offset:32
	global_load_dwordx4 v[200:203], v[112:113], off
	global_load_dwordx4 v[204:207], v[112:113], off offset:16
	s_add_i32 s17, 0, 0x18800
	v_add3_u32 v108, s17, v194, v96
	ds_read_b128 v[96:99], v108
	ds_read_b128 v[100:103], v108 offset:16
	ds_read_b128 v[104:107], v108 offset:32
	ds_read_b128 v[108:111], v108 offset:48
	s_movk_i32 s17, 0x1ff
	v_cmp_lt_i32_e32 vcc, s17, v71
	v_add_u32_e32 v70, 0x1000, v70
	s_waitcnt lgkmcnt(1)
	v_mov_b32_e32 v120, v105
	v_mov_b32_e32 v121, v106
	v_mov_b32_e32 v116, v104
	v_mov_b32_e32 v117, v107
	s_or_b64 s[6:7], vcc, s[6:7]
	s_waitcnt vmcnt(0)
	v_mov_b32_e32 v118, v92
	v_mov_b32_e32 v119, v95
	v_mov_b32_e32 v114, v93
	v_mov_b32_e32 v115, v94
	v_pk_mul_f32 v[118:119], v[118:119], v[120:121]
	s_waitcnt lgkmcnt(0)
	v_mov_b32_e32 v120, v109
	v_pk_fma_f32 v[114:115], v[114:115], v[116:117], v[118:119]
	v_mov_b32_e32 v118, v88
	v_mov_b32_e32 v119, v91
	v_mov_b32_e32 v121, v110
	v_pk_add_f32 v[116:117], v[76:77], v[114:115]
	v_mov_b32_e32 v76, v89
	v_mov_b32_e32 v77, v90
	v_mov_b32_e32 v114, v108
	v_mov_b32_e32 v115, v111
	v_pk_mul_f32 v[118:119], v[118:119], v[120:121]
	v_pk_mul_f32 v[94:95], v[94:95], v[106:107]
	v_pk_fma_f32 v[76:77], v[76:77], v[114:115], v[118:119]
	v_pk_mul_f32 v[92:93], v[92:93], v[104:105]
	v_pk_add_f32 v[118:119], v[78:79], v[76:77]
	v_mov_b32_e32 v104, v92
	v_mov_b32_e32 v105, v94
	v_mov_b32_e32 v94, v93
	v_pk_mul_f32 v[90:91], v[90:91], v[110:111]
	v_pk_mul_f32 v[88:89], v[88:89], v[108:109]
	v_pk_add_f32 v[92:93], v[104:105], v[94:95] neg_lo:[0,1] neg_hi:[0,1]
	v_mov_b32_e32 v94, v88
	v_mov_b32_e32 v95, v90
	v_mov_b32_e32 v90, v89
	v_mov_b32_e32 v104, v84
	v_mov_b32_e32 v105, v87
	v_mov_b32_e32 v106, v97
	v_mov_b32_e32 v107, v98
	v_pk_add_f32 v[88:89], v[94:95], v[90:91] neg_lo:[0,1] neg_hi:[0,1]
	v_mov_b32_e32 v90, v85
	v_mov_b32_e32 v91, v86
	v_mov_b32_e32 v94, v96
	v_mov_b32_e32 v95, v99
	v_pk_mul_f32 v[104:105], v[104:105], v[106:107]
	v_mov_b32_e32 v106, v101
	v_pk_fma_f32 v[90:91], v[90:91], v[94:95], v[104:105]
	v_mov_b32_e32 v104, v80
	v_mov_b32_e32 v105, v83
	v_mov_b32_e32 v107, v102
	v_pk_add_f32 v[90:91], v[72:73], v[90:91]
	v_mov_b32_e32 v72, v81
	v_mov_b32_e32 v73, v82
	v_mov_b32_e32 v94, v100
	v_mov_b32_e32 v95, v103
	v_pk_mul_f32 v[104:105], v[104:105], v[106:107]
	s_waitcnt vmcnt(0)
	v_pk_add_f32 v[92:93], v[92:93], v[204:205]
	v_pk_fma_f32 v[72:73], v[72:73], v[94:95], v[104:105]
	v_pk_add_f32 v[88:89], v[206:207], v[88:89]
	v_pk_add_f32 v[94:95], v[74:75], v[72:73]
	v_pk_mul_f32 v[72:73], v[86:87], v[98:99]
	v_pk_mul_f32 v[74:75], v[84:85], v[96:97]
	v_mov_b32_e32 v85, v72
	v_mov_b32_e32 v84, v74
	v_mov_b32_e32 v72, v75
	v_pk_add_f32 v[72:73], v[84:85], v[72:73] neg_lo:[0,1] neg_hi:[0,1]
	v_pk_mul_f32 v[74:75], v[82:83], v[102:103]
	v_pk_add_f32 v[72:73], v[72:73], v[200:201]
	v_pk_mul_f32 v[76:77], v[80:81], v[100:101]
	v_mov_b32_e32 v81, v74
	v_mov_b32_e32 v80, v76
	v_mov_b32_e32 v74, v77
	v_pk_add_f32 v[74:75], v[80:81], v[74:75] neg_lo:[0,1] neg_hi:[0,1]
	v_lshlrev_b32_e32 v81, 1, v124
	v_pk_add_f32 v[74:75], v[202:203], v[74:75]
	v_mul_lo_u32 v80, v123, s24
	v_lshl_or_b32 v81, v122, 8, v81
	v_cvt_pk_bf16_f32 v72, v72, v73
	v_cvt_pk_bf16_f32 v73, v74, v75
	v_cvt_pk_bf16_f32 v74, v92, v93
	v_cvt_pk_bf16_f32 v75, v88, v89
	v_add3_u32 v80, 0, v80, v81
	v_cvt_pk_bf16_f32 v76, v90, v91
	v_cvt_pk_bf16_f32 v77, v94, v95
	v_cvt_pk_bf16_f32 v78, v116, v117
	v_cvt_pk_bf16_f32 v79, v118, v119
	ds_write_b128 v80, v[72:75] offset:512
	ds_write_b128 v80, v[76:79] offset:640
	v_add_u32_e32 v72, 0x200, v71
	v_mov_b32_e32 v71, v72
	s_andn2_b64 exec, exec, s[6:7]
	s_cbranch_execnz .LBB0_1613
	s_branch .LBB0_1580

; #define LAS __attribute__((address_space(3)))
; __device__ __forceinline__ void glu_item(Frame& F, const Args& AR, int l, int item) {
;     ...
;     bf16x8v b0[8][2];
;     wave_bfrags<K>(Bt, 0, b0, F.lane);
;     __syncthreads();
;     for (int idx = F.tid; idx < 80 * 64; idx += NTHR) { const int pc = idx & 63, row = idx >> 6;
;         v4u v = {0u, 0u, 0u, 0u}; if (row < NROW) v = *(const v4u*)(YG + (size_t)(row0 + row) * 512 + pc * 8);
;         *(LAS v4u*)(at + row * LDA + pc * 16) = v; }
;     bf16x8v b1[8][2]; wave_bfrags<K>(Bt, 1, b1, F.lane);
.LBB0_1674:
	s_lshl_b32 s4, s13, 8
	s_and_b32 s4, s4, 0x100
	s_add_i32 s4, s4, s12
	s_ashr_i32 s5, s4, 31
	s_lshl_b64 s[6:7], s[4:5], 10
	v_lshl_add_u64 v[6:7], v[134:135], 0, s[6:7]
	v_lshl_add_u64 v[30:31], v[6:7], 0, v[194:195]
	v_mov_b32_e32 v137, v195
	v_lshl_add_u64 v[2:3], v[6:7], 0, v[136:137]
	global_load_dwordx4 v[122:125], v[30:31], off
	global_load_dwordx4 v[114:117], v[30:31], off offset:64
	global_load_dwordx4 v[126:129], v[2:3], off
	global_load_dwordx4 v[118:121], v[2:3], off offset:64
	global_load_dwordx4 v[106:109], v[30:31], off offset:128
	global_load_dwordx4 v[98:101], v[30:31], off offset:192
	global_load_dwordx4 v[110:113], v[2:3], off offset:128
	global_load_dwordx4 v[102:105], v[2:3], off offset:192
	global_load_dwordx4 v[90:93], v[30:31], off offset:256
	global_load_dwordx4 v[82:85], v[30:31], off offset:320
	global_load_dwordx4 v[94:97], v[2:3], off offset:256
	global_load_dwordx4 v[86:89], v[2:3], off offset:320
	global_load_dwordx4 v[74:77], v[30:31], off offset:384
	global_load_dwordx4 v[58:61], v[30:31], off offset:448
	global_load_dwordx4 v[78:81], v[2:3], off offset:384
	global_load_dwordx4 v[62:65], v[2:3], off offset:448
	s_lshr_b32 s5, s13, 1
	s_mulk_i32 s5, 0x44
	s_barrier
	s_and_saveexec_b64 s[6:7], s[38:39]
	s_cbranch_execz .LBB0_1679
	v_ashrrev_i32_e32 v9, 6, v133
	v_add_u32_e32 v2, s5, v9
	v_ashrrev_i32_e32 v3, 31, v2
	v_lshlrev_b64 v[2:3], 10, v[2:3]
	v_lshl_add_u64 v[2:3], v[130:131], 0, v[2:3]
	s_mov_b64 s[8:9], 0x2000
	global_load_dwordx4 v[12:15], v[2:3], off
	v_lshl_add_u64 v[2:3], v[2:3], 0, s[8:9]
	global_load_dwordx4 v[16:19], v[2:3], off
	v_lshl_add_u64 v[2:3], v[2:3], 0, s[8:9]
	global_load_dwordx4 v[20:23], v[2:3], off
	v_lshl_add_u64 v[2:3], v[2:3], 0, s[8:9]
	global_load_dwordx4 v[24:27], v[2:3], off
	v_lshl_add_u64 v[2:3], v[2:3], 0, s[8:9]
	global_load_dwordx4 v[32:35], v[2:3], off
	v_lshl_add_u64 v[2:3], v[2:3], 0, s[8:9]
	global_load_dwordx4 v[36:39], v[2:3], off
	v_lshl_add_u64 v[2:3], v[2:3], 0, s[8:9]
	global_load_dwordx4 v[40:43], v[2:3], off
	v_lshl_add_u64 v[2:3], v[2:3], 0, s[8:9]
	global_load_dwordx4 v[44:47], v[2:3], off
	v_lshl_add_u64 v[2:3], v[2:3], 0, s[8:9]
	global_load_dwordx4 v[48:51], v[2:3], off
	v_mad_u32_u24 v10, v9, s24, v132
	v_add_u32_e32 v11, 0x10400, v10
	v_mov_b32_e32 v52, 0
	v_mov_b32_e32 v53, 0
	v_mov_b32_e32 v54, 0
	v_mov_b32_e32 v55, 0
	v_cmp_gt_u32_e32 vcc, 4, v9
	s_waitcnt vmcnt(8)
	ds_write_b128 v10, v[12:15]
	s_waitcnt vmcnt(7)
	ds_write_b128 v10, v[16:19] offset:8320
	s_waitcnt vmcnt(6)
	ds_write_b128 v10, v[20:23] offset:16640
	s_waitcnt vmcnt(5)
	ds_write_b128 v10, v[24:27] offset:24960
	s_waitcnt vmcnt(4)
	ds_write_b128 v10, v[32:35] offset:33280
	s_waitcnt vmcnt(3)
	ds_write_b128 v10, v[36:39] offset:41600
	s_waitcnt vmcnt(2)
	ds_write_b128 v10, v[40:43] offset:49920
	s_waitcnt vmcnt(1)
	ds_write_b128 v10, v[44:47] offset:58240
	s_waitcnt vmcnt(0)
	v_cndmask_b32_e32 v48, 0, v48, vcc
	v_cndmask_b32_e32 v49, 0, v49, vcc
	v_cndmask_b32_e32 v50, 0, v50, vcc
	v_cndmask_b32_e32 v51, 0, v51, vcc
	ds_write_b128 v11, v[48:51]
	ds_write_b128 v11, v[52:55] offset:8320
.LBB0_1679:
	s_or_b64 exec, exec, s[6:7]
	s_waitcnt vmcnt(0)
	v_mov_b32_e32 v137, v195
	v_lshl_add_u64 v[32:33], v[6:7], 0, v[136:137]
	v_add_u32_e32 v137, v139, v140
	global_load_dwordx4 v[66:69], v[30:31], off offset:512
	global_load_dwordx4 v[70:73], v[32:33], off offset:512
	global_load_dwordx4 v[50:53], v[30:31], off offset:576
	global_load_dwordx4 v[54:57], v[32:33], off offset:576
	global_load_dwordx4 v[42:45], v[30:31], off offset:640
	global_load_dwordx4 v[46:49], v[32:33], off offset:640
	global_load_dwordx4 v[34:37], v[30:31], off offset:704
	global_load_dwordx4 v[38:41], v[32:33], off offset:704
	global_load_dwordx4 v[22:25], v[30:31], off offset:768
	global_load_dwordx4 v[26:29], v[32:33], off offset:768
	global_load_dwordx4 v[14:17], v[30:31], off offset:832
	global_load_dwordx4 v[18:21], v[32:33], off offset:832
	global_load_dwordx4 v[6:9], v[30:31], off offset:896
	global_load_dwordx4 v[10:13], v[32:33], off offset:896
	global_load_dwordx4 v[2:5], v[30:31], off offset:960
	s_nop 0
	global_load_dwordx4 v[30:33], v[32:33], off offset:960
	s_waitcnt lgkmcnt(0)
	s_barrier
	ds_read_b128 v[148:151], v137
	ds_read_b128 v[156:159], v137 offset:16640
	ds_read_b128 v[164:167], v137 offset:33280
	ds_read_b128 v[172:175], v137 offset:49920
	ds_read_b128 v[180:183], v147
	s_waitcnt lgkmcnt(4)
	v_mfma_f32_16x16x32_bf16 v[152:155], v[122:125], v[148:151], 0
	v_mfma_f32_16x16x32_bf16 v[148:151], v[126:129], v[148:151], 0
	s_waitcnt lgkmcnt(3)
	v_mfma_f32_16x16x32_bf16 v[160:163], v[122:125], v[156:159], 0
	v_mfma_f32_16x16x32_bf16 v[156:159], v[126:129], v[156:159], 0
	s_waitcnt lgkmcnt(2)
	v_mfma_f32_16x16x32_bf16 v[168:171], v[122:125], v[164:167], 0
	v_mfma_f32_16x16x32_bf16 v[164:167], v[126:129], v[164:167], 0
	s_waitcnt lgkmcnt(1)
	v_mfma_f32_16x16x32_bf16 v[176:179], v[122:125], v[172:175], 0
	v_mfma_f32_16x16x32_bf16 v[172:175], v[126:129], v[172:175], 0
	s_waitcnt lgkmcnt(0)
	v_mfma_f32_16x16x32_bf16 v[122:125], v[122:125], v[180:183], 0
	v_mfma_f32_16x16x32_bf16 v[126:129], v[126:129], v[180:183], 0
	ds_read_b128 v[180:183], v137 offset:64
	s_waitcnt lgkmcnt(0)
	v_mfma_f32_16x16x32_bf16 v[152:155], v[114:117], v[180:183], v[152:155]
	v_mfma_f32_16x16x32_bf16 v[148:151], v[118:121], v[180:183], v[148:151]
	ds_read_b128 v[180:183], v137 offset:16704
	s_waitcnt lgkmcnt(0)
	v_mfma_f32_16x16x32_bf16 v[160:163], v[114:117], v[180:183], v[160:163]
	v_mfma_f32_16x16x32_bf16 v[156:159], v[118:121], v[180:183], v[156:159]
	ds_read_b128 v[180:183], v137 offset:33344
	s_waitcnt lgkmcnt(0)
; #define LAS __attribute__((address_space(3)))
; template <int K, int MT> __device__ __forceinline__ void wave_mma_batch(const LAS unsigned char* a_lds, int lda, int kb, const bf16x8v (&bfr)[8][2], f32x4 (&acc)[MT][2], int lane) {
;     const int fr = lane & 15, fq = lane >> 4;
; #pragma unroll
;     for (int ks = 0; ks < 8; ++ks)
; #pragma unroll
;         for (int m = 0; m < MT; ++m) { const bf16x8v af = *(const LAS bf16x8v*)(a_lds + (m * 16 + fr) * lda + (kb * 256 + ks * 32 + 8 * fq) * 2);
; #pragma unroll
;             for (int n = 0; n < 2; ++n) acc[m][n] = __builtin_amdgcn_mfma_f32_16x16x32_bf16(bfr[ks][n], af, acc[m][n], 0, 0, 0); }
; }
	v_mfma_f32_16x16x32_bf16 v[168:171], v[114:117], v[180:183], v[168:171]
	v_mfma_f32_16x16x32_bf16 v[164:167], v[118:121], v[180:183], v[164:167]
	ds_read_b128 v[180:183], v137 offset:49984
	s_waitcnt lgkmcnt(0)
	v_mfma_f32_16x16x32_bf16 v[176:179], v[114:117], v[180:183], v[176:179]
	v_mfma_f32_16x16x32_bf16 v[172:175], v[118:121], v[180:183], v[172:175]
	ds_read_b128 v[180:183], v147 offset:64
	s_waitcnt lgkmcnt(0)
	v_mfma_f32_16x16x32_bf16 v[114:117], v[114:117], v[180:183], v[122:125]
	s_nop 2
	ds_read_b128 v[122:125], v137 offset:128
	v_mfma_f32_16x16x32_bf16 v[118:121], v[118:121], v[180:183], v[126:129]
	s_waitcnt lgkmcnt(0)
	v_mfma_f32_16x16x32_bf16 v[126:129], v[106:109], v[122:125], v[152:155]
	v_mfma_f32_16x16x32_bf16 v[122:125], v[110:113], v[122:125], v[148:151]
	s_nop 2
	ds_read_b128 v[148:151], v137 offset:16768
	s_waitcnt lgkmcnt(0)
	v_mfma_f32_16x16x32_bf16 v[152:155], v[106:109], v[148:151], v[160:163]
	v_mfma_f32_16x16x32_bf16 v[148:151], v[110:113], v[148:151], v[156:159]
	s_nop 2
	ds_read_b128 v[156:159], v137 offset:33408
	s_waitcnt lgkmcnt(0)
	v_mfma_f32_16x16x32_bf16 v[160:163], v[106:109], v[156:159], v[168:171]
	v_mfma_f32_16x16x32_bf16 v[156:159], v[110:113], v[156:159], v[164:167]
	s_nop 2
	ds_read_b128 v[164:167], v137 offset:50048
	s_waitcnt lgkmcnt(0)
	v_mfma_f32_16x16x32_bf16 v[168:171], v[106:109], v[164:167], v[176:179]
	v_mfma_f32_16x16x32_bf16 v[164:167], v[110:113], v[164:167], v[172:175]
	s_nop 2
	ds_read_b128 v[172:175], v147 offset:128
	s_waitcnt lgkmcnt(0)
	v_mfma_f32_16x16x32_bf16 v[106:109], v[106:109], v[172:175], v[114:117]
	s_nop 2
	ds_read_b128 v[114:117], v137 offset:192
	v_mfma_f32_16x16x32_bf16 v[110:113], v[110:113], v[172:175], v[118:121]
	s_waitcnt lgkmcnt(0)
	v_mfma_f32_16x16x32_bf16 v[118:121], v[98:101], v[114:117], v[126:129]
	v_mfma_f32_16x16x32_bf16 v[114:117], v[102:105], v[114:117], v[122:125]
	s_nop 2
	ds_read_b128 v[122:125], v137 offset:16832
	s_waitcnt lgkmcnt(0)
	v_mfma_f32_16x16x32_bf16 v[126:129], v[98:101], v[122:125], v[152:155]
	v_mfma_f32_16x16x32_bf16 v[122:125], v[102:105], v[122:125], v[148:151]
	s_nop 2
	ds_read_b128 v[148:151], v137 offset:33472
	s_waitcnt lgkmcnt(0)
	v_mfma_f32_16x16x32_bf16 v[152:155], v[98:101], v[148:151], v[160:163]
	v_mfma_f32_16x16x32_bf16 v[148:151], v[102:105], v[148:151], v[156:159]
	s_nop 2
	ds_read_b128 v[156:159], v137 offset:50112
	s_waitcnt lgkmcnt(0)
	v_mfma_f32_16x16x32_bf16 v[160:163], v[98:101], v[156:159], v[168:171]
	v_mfma_f32_16x16x32_bf16 v[156:159], v[102:105], v[156:159], v[164:167]
	s_nop 2
	ds_read_b128 v[164:167], v147 offset:192
	s_waitcnt lgkmcnt(0)
	v_mfma_f32_16x16x32_bf16 v[98:101], v[98:101], v[164:167], v[106:109]
	s_nop 2
	ds_read_b128 v[106:109], v137 offset:256
	v_mfma_f32_16x16x32_bf16 v[102:105], v[102:105], v[164:167], v[110:113]
	s_waitcnt lgkmcnt(0)
	v_mfma_f32_16x16x32_bf16 v[110:113], v[90:93], v[106:109], v[118:121]
	v_mfma_f32_16x16x32_bf16 v[106:109], v[94:97], v[106:109], v[114:117]
	s_nop 2
	ds_read_b128 v[114:117], v137 offset:16896
	s_waitcnt lgkmcnt(0)
	v_mfma_f32_16x16x32_bf16 v[118:121], v[90:93], v[114:117], v[126:129]
	v_mfma_f32_16x16x32_bf16 v[114:117], v[94:97], v[114:117], v[122:125]
	s_nop 2
	ds_read_b128 v[122:125], v137 offset:33536
	s_waitcnt lgkmcnt(0)
	v_mfma_f32_16x16x32_bf16 v[126:129], v[90:93], v[122:125], v[152:155]
	v_mfma_f32_16x16x32_bf16 v[122:125], v[94:97], v[122:125], v[148:151]
	s_nop 2
	ds_read_b128 v[148:151], v137 offset:50176
	s_waitcnt lgkmcnt(0)
	v_mfma_f32_16x16x32_bf16 v[152:155], v[90:93], v[148:151], v[160:163]
	v_mfma_f32_16x16x32_bf16 v[148:151], v[94:97], v[148:151], v[156:159]
	s_nop 2
	ds_read_b128 v[156:159], v147 offset:256
	s_waitcnt lgkmcnt(0)
	v_mfma_f32_16x16x32_bf16 v[90:93], v[90:93], v[156:159], v[98:101]
	s_nop 2
	ds_read_b128 v[98:101], v137 offset:320
	v_mfma_f32_16x16x32_bf16 v[94:97], v[94:97], v[156:159], v[102:105]
	s_waitcnt lgkmcnt(0)
	v_mfma_f32_16x16x32_bf16 v[102:105], v[82:85], v[98:101], v[110:113]
	v_mfma_f32_16x16x32_bf16 v[98:101], v[86:89], v[98:101], v[106:109]
	s_nop 2
	ds_read_b128 v[106:109], v137 offset:16960
	s_waitcnt lgkmcnt(0)
	v_mfma_f32_16x16x32_bf16 v[110:113], v[82:85], v[106:109], v[118:121]
	v_mfma_f32_16x16x32_bf16 v[106:109], v[86:89], v[106:109], v[114:117]
	s_nop 2
	ds_read_b128 v[114:117], v137 offset:33600
	s_waitcnt lgkmcnt(0)
	v_mfma_f32_16x16x32_bf16 v[118:121], v[82:85], v[114:117], v[126:129]
	v_mfma_f32_16x16x32_bf16 v[114:117], v[86:89], v[114:117], v[122:125]
	s_nop 2
	ds_read_b128 v[122:125], v137 offset:50240
	s_waitcnt lgkmcnt(0)
	v_mfma_f32_16x16x32_bf16 v[126:129], v[82:85], v[122:125], v[152:155]
	v_mfma_f32_16x16x32_bf16 v[122:125], v[86:89], v[122:125], v[148:151]
	s_nop 2
	ds_read_b128 v[148:151], v147 offset:320
	s_waitcnt lgkmcnt(0)
	v_mfma_f32_16x16x32_bf16 v[82:85], v[82:85], v[148:151], v[90:93]
	s_nop 2
	ds_read_b128 v[90:93], v137 offset:384
	v_mfma_f32_16x16x32_bf16 v[86:89], v[86:89], v[148:151], v[94:97]
	s_waitcnt lgkmcnt(0)
	v_mfma_f32_16x16x32_bf16 v[94:97], v[74:77], v[90:93], v[102:105]
	v_mfma_f32_16x16x32_bf16 v[90:93], v[78:81], v[90:93], v[98:101]
	s_nop 2
	ds_read_b128 v[98:101], v137 offset:17024
	s_waitcnt lgkmcnt(0)
	v_mfma_f32_16x16x32_bf16 v[102:105], v[74:77], v[98:101], v[110:113]
	v_mfma_f32_16x16x32_bf16 v[98:101], v[78:81], v[98:101], v[106:109]
	s_nop 2
	ds_read_b128 v[106:109], v137 offset:33664
	s_waitcnt lgkmcnt(0)
	v_mfma_f32_16x16x32_bf16 v[110:113], v[74:77], v[106:109], v[118:121]
	v_mfma_f32_16x16x32_bf16 v[106:109], v[78:81], v[106:109], v[114:117]
	s_nop 2
	ds_read_b128 v[114:117], v137 offset:50304
	s_waitcnt lgkmcnt(0)
; #define LAS __attribute__((address_space(3)))
; template <int K, int MT> __device__ __forceinline__ void wave_mma_batch(const LAS unsigned char* a_lds, int lda, int kb, const bf16x8v (&bfr)[8][2], f32x4 (&acc)[MT][2], int lane) {
;     const int fr = lane & 15, fq = lane >> 4;
; #pragma unroll
;     for (int ks = 0; ks < 8; ++ks)
; #pragma unroll
;         for (int m = 0; m < MT; ++m) { const bf16x8v af = *(const LAS bf16x8v*)(a_lds + (m * 16 + fr) * lda + (kb * 256 + ks * 32 + 8 * fq) * 2);
; #pragma unroll
;             for (int n = 0; n < 2; ++n) acc[m][n] = __builtin_amdgcn_mfma_f32_16x16x32_bf16(bfr[ks][n], af, acc[m][n], 0, 0, 0); }
; }
	v_mfma_f32_16x16x32_bf16 v[118:121], v[74:77], v[114:117], v[126:129]
	v_mfma_f32_16x16x32_bf16 v[114:117], v[78:81], v[114:117], v[122:125]
	s_nop 2
	ds_read_b128 v[122:125], v147 offset:384
	s_waitcnt lgkmcnt(0)
	v_mfma_f32_16x16x32_bf16 v[74:77], v[74:77], v[122:125], v[82:85]
	s_nop 2
	ds_read_b128 v[82:85], v137 offset:448
	v_mfma_f32_16x16x32_bf16 v[78:81], v[78:81], v[122:125], v[86:89]
	s_waitcnt lgkmcnt(0)
	v_mfma_f32_16x16x32_bf16 v[86:89], v[58:61], v[82:85], v[94:97]
	v_mfma_f32_16x16x32_bf16 v[82:85], v[62:65], v[82:85], v[90:93]
	s_nop 2
	ds_read_b128 v[90:93], v137 offset:17088
	s_waitcnt lgkmcnt(0)
	v_mfma_f32_16x16x32_bf16 v[94:97], v[58:61], v[90:93], v[102:105]
	v_mfma_f32_16x16x32_bf16 v[90:93], v[62:65], v[90:93], v[98:101]
	s_nop 2
	ds_read_b128 v[98:101], v137 offset:33728
	s_waitcnt lgkmcnt(0)
	v_mfma_f32_16x16x32_bf16 v[102:105], v[58:61], v[98:101], v[110:113]
	v_mfma_f32_16x16x32_bf16 v[98:101], v[62:65], v[98:101], v[106:109]
	s_nop 2
	ds_read_b128 v[106:109], v137 offset:50368
	s_waitcnt lgkmcnt(0)
	v_mfma_f32_16x16x32_bf16 v[110:113], v[58:61], v[106:109], v[118:121]
	v_mfma_f32_16x16x32_bf16 v[106:109], v[62:65], v[106:109], v[114:117]
	s_nop 2
	ds_read_b128 v[114:117], v147 offset:448
	s_waitcnt lgkmcnt(0)
	v_mfma_f32_16x16x32_bf16 v[58:61], v[58:61], v[114:117], v[74:77]
	s_nop 2
	ds_read_b128 v[74:77], v137 offset:512
	v_mfma_f32_16x16x32_bf16 v[62:65], v[62:65], v[114:117], v[78:81]
	s_waitcnt vmcnt(15) lgkmcnt(0)
	v_mfma_f32_16x16x32_bf16 v[78:81], v[66:69], v[74:77], v[86:89]
	s_waitcnt vmcnt(14)
	v_mfma_f32_16x16x32_bf16 v[74:77], v[70:73], v[74:77], v[82:85]
	s_nop 2
	ds_read_b128 v[82:85], v137 offset:17152
	s_waitcnt lgkmcnt(0)
	v_mfma_f32_16x16x32_bf16 v[86:89], v[66:69], v[82:85], v[94:97]
	v_mfma_f32_16x16x32_bf16 v[82:85], v[70:73], v[82:85], v[90:93]
	s_nop 2
	ds_read_b128 v[90:93], v137 offset:33792
	s_waitcnt lgkmcnt(0)
	v_mfma_f32_16x16x32_bf16 v[94:97], v[66:69], v[90:93], v[102:105]
	v_mfma_f32_16x16x32_bf16 v[90:93], v[70:73], v[90:93], v[98:101]
	s_nop 2
	ds_read_b128 v[98:101], v137 offset:50432
	s_waitcnt lgkmcnt(0)
	v_mfma_f32_16x16x32_bf16 v[102:105], v[66:69], v[98:101], v[110:113]
	v_mfma_f32_16x16x32_bf16 v[98:101], v[70:73], v[98:101], v[106:109]
	s_nop 2
	ds_read_b128 v[106:109], v147 offset:512
	s_waitcnt lgkmcnt(0)
	v_mfma_f32_16x16x32_bf16 v[58:61], v[66:69], v[106:109], v[58:61]
	ds_read_b128 v[66:69], v137 offset:576
	v_mfma_f32_16x16x32_bf16 v[62:65], v[70:73], v[106:109], v[62:65]
	s_waitcnt vmcnt(13) lgkmcnt(0)
	v_mfma_f32_16x16x32_bf16 v[70:73], v[50:53], v[66:69], v[78:81]
	s_waitcnt vmcnt(12)
	v_mfma_f32_16x16x32_bf16 v[66:69], v[54:57], v[66:69], v[74:77]
	s_nop 2
	ds_read_b128 v[74:77], v137 offset:17216
	s_waitcnt lgkmcnt(0)
	v_mfma_f32_16x16x32_bf16 v[78:81], v[50:53], v[74:77], v[86:89]
	v_mfma_f32_16x16x32_bf16 v[74:77], v[54:57], v[74:77], v[82:85]
	s_nop 2
	ds_read_b128 v[82:85], v137 offset:33856
	s_waitcnt lgkmcnt(0)
	v_mfma_f32_16x16x32_bf16 v[86:89], v[50:53], v[82:85], v[94:97]
	v_mfma_f32_16x16x32_bf16 v[82:85], v[54:57], v[82:85], v[90:93]
	s_nop 2
	ds_read_b128 v[90:93], v137 offset:50496
	s_waitcnt lgkmcnt(0)
	v_mfma_f32_16x16x32_bf16 v[94:97], v[50:53], v[90:93], v[102:105]
	v_mfma_f32_16x16x32_bf16 v[90:93], v[54:57], v[90:93], v[98:101]
	s_nop 2
	ds_read_b128 v[98:101], v147 offset:576
	s_waitcnt lgkmcnt(0)
	v_mfma_f32_16x16x32_bf16 v[50:53], v[50:53], v[98:101], v[58:61]
	s_nop 2
	ds_read_b128 v[58:61], v137 offset:640
	v_mfma_f32_16x16x32_bf16 v[54:57], v[54:57], v[98:101], v[62:65]
	s_waitcnt vmcnt(11) lgkmcnt(0)
	v_mfma_f32_16x16x32_bf16 v[62:65], v[42:45], v[58:61], v[70:73]
	s_waitcnt vmcnt(10)
	v_mfma_f32_16x16x32_bf16 v[58:61], v[46:49], v[58:61], v[66:69]
	s_nop 2
	ds_read_b128 v[66:69], v137 offset:17280
	s_waitcnt lgkmcnt(0)
	v_mfma_f32_16x16x32_bf16 v[70:73], v[42:45], v[66:69], v[78:81]
	v_mfma_f32_16x16x32_bf16 v[66:69], v[46:49], v[66:69], v[74:77]
	s_nop 2
	ds_read_b128 v[74:77], v137 offset:33920
	s_waitcnt lgkmcnt(0)
	v_mfma_f32_16x16x32_bf16 v[78:81], v[42:45], v[74:77], v[86:89]
	v_mfma_f32_16x16x32_bf16 v[74:77], v[46:49], v[74:77], v[82:85]
	s_nop 2
	ds_read_b128 v[82:85], v137 offset:50560
	s_waitcnt lgkmcnt(0)
	v_mfma_f32_16x16x32_bf16 v[86:89], v[42:45], v[82:85], v[94:97]
	v_mfma_f32_16x16x32_bf16 v[82:85], v[46:49], v[82:85], v[90:93]
	s_nop 2
	ds_read_b128 v[90:93], v147 offset:640
	s_waitcnt lgkmcnt(0)
	v_mfma_f32_16x16x32_bf16 v[42:45], v[42:45], v[90:93], v[50:53]
	s_nop 2
	ds_read_b128 v[50:53], v137 offset:704
	v_mfma_f32_16x16x32_bf16 v[46:49], v[46:49], v[90:93], v[54:57]
	s_waitcnt vmcnt(9) lgkmcnt(0)
	v_mfma_f32_16x16x32_bf16 v[54:57], v[34:37], v[50:53], v[62:65]
	s_waitcnt vmcnt(8)
	v_mfma_f32_16x16x32_bf16 v[50:53], v[38:41], v[50:53], v[58:61]
	s_nop 2
	ds_read_b128 v[58:61], v137 offset:17344
	s_waitcnt lgkmcnt(0)
	v_mfma_f32_16x16x32_bf16 v[62:65], v[34:37], v[58:61], v[70:73]
	v_mfma_f32_16x16x32_bf16 v[58:61], v[38:41], v[58:61], v[66:69]
	s_nop 2
	ds_read_b128 v[66:69], v137 offset:33984
	s_waitcnt lgkmcnt(0)
	v_mfma_f32_16x16x32_bf16 v[70:73], v[34:37], v[66:69], v[78:81]
	v_mfma_f32_16x16x32_bf16 v[66:69], v[38:41], v[66:69], v[74:77]
	s_nop 2
	ds_read_b128 v[74:77], v137 offset:50624
	s_waitcnt lgkmcnt(0)
	v_mfma_f32_16x16x32_bf16 v[78:81], v[34:37], v[74:77], v[86:89]
	v_mfma_f32_16x16x32_bf16 v[74:77], v[38:41], v[74:77], v[82:85]
	s_nop 2
	ds_read_b128 v[82:85], v147 offset:704
	s_waitcnt lgkmcnt(0)
	v_mfma_f32_16x16x32_bf16 v[34:37], v[34:37], v[82:85], v[42:45]
	s_nop 2
	ds_read_b128 v[42:45], v137 offset:768
	v_mfma_f32_16x16x32_bf16 v[38:41], v[38:41], v[82:85], v[46:49]
	s_waitcnt vmcnt(7) lgkmcnt(0)
; #define LAS __attribute__((address_space(3)))
; __device__ __forceinline__ void glu_item(Frame& F, const Args& AR, int l, int item) {
;     ...
;     { wave_mma_batch<K, MT>(at, LDA, 0, b0, acc, F.lane); wave_mma_batch<K, MT>(at, LDA, 1, b1, acc, F.lane); }
;     const int fr = F.lane & 15, fq = F.lane >> 4;
; #pragma unroll
;     for (int n = 0; n < 2; ++n) { const int col = colw + n * 16 + 4 * fq; const f32x4 bias = *(const f32x4*)(AR.in[I_GLUB] + l * 512 + col);
; #pragma unroll
;         for (int m = 0; m < MT; ++m) { const int row = m * 16 + fr;
;             if (row < NROW) { const v2u yw = *(const LAS v2u*)(at + row * LDA + col * 2); const f32x4 z = acc[m][n] + bias;
	v_mfma_f32_16x16x32_bf16 v[46:49], v[22:25], v[42:45], v[54:57]
	s_waitcnt vmcnt(6)
	v_mfma_f32_16x16x32_bf16 v[42:45], v[26:29], v[42:45], v[50:53]
	s_nop 2
	ds_read_b128 v[50:53], v137 offset:17408
	s_waitcnt lgkmcnt(0)
	v_mfma_f32_16x16x32_bf16 v[54:57], v[22:25], v[50:53], v[62:65]
	v_mfma_f32_16x16x32_bf16 v[50:53], v[26:29], v[50:53], v[58:61]
	s_nop 2
	ds_read_b128 v[58:61], v137 offset:34048
	s_waitcnt lgkmcnt(0)
	v_mfma_f32_16x16x32_bf16 v[62:65], v[22:25], v[58:61], v[70:73]
	v_mfma_f32_16x16x32_bf16 v[58:61], v[26:29], v[58:61], v[66:69]
	s_nop 2
	ds_read_b128 v[66:69], v137 offset:50688
	s_waitcnt lgkmcnt(0)
	v_mfma_f32_16x16x32_bf16 v[70:73], v[22:25], v[66:69], v[78:81]
	v_mfma_f32_16x16x32_bf16 v[66:69], v[26:29], v[66:69], v[74:77]
	s_nop 2
	ds_read_b128 v[74:77], v147 offset:768
	s_waitcnt lgkmcnt(0)
	v_mfma_f32_16x16x32_bf16 v[22:25], v[22:25], v[74:77], v[34:37]
	s_nop 2
	ds_read_b128 v[34:37], v137 offset:832
	v_mfma_f32_16x16x32_bf16 v[26:29], v[26:29], v[74:77], v[38:41]
	s_waitcnt vmcnt(5) lgkmcnt(0)
	v_mfma_f32_16x16x32_bf16 v[38:41], v[14:17], v[34:37], v[46:49]
	s_waitcnt vmcnt(4)
	v_mfma_f32_16x16x32_bf16 v[34:37], v[18:21], v[34:37], v[42:45]
	s_nop 2
	ds_read_b128 v[42:45], v137 offset:17472
	s_waitcnt lgkmcnt(0)
	v_mfma_f32_16x16x32_bf16 v[46:49], v[14:17], v[42:45], v[54:57]
	v_mfma_f32_16x16x32_bf16 v[42:45], v[18:21], v[42:45], v[50:53]
	s_nop 2
	ds_read_b128 v[50:53], v137 offset:34112
	s_waitcnt lgkmcnt(0)
	v_mfma_f32_16x16x32_bf16 v[54:57], v[14:17], v[50:53], v[62:65]
	v_mfma_f32_16x16x32_bf16 v[50:53], v[18:21], v[50:53], v[58:61]
	s_nop 2
	ds_read_b128 v[58:61], v137 offset:50752
	s_waitcnt lgkmcnt(0)
	v_mfma_f32_16x16x32_bf16 v[62:65], v[14:17], v[58:61], v[70:73]
	v_mfma_f32_16x16x32_bf16 v[58:61], v[18:21], v[58:61], v[66:69]
	s_nop 2
	ds_read_b128 v[66:69], v147 offset:832
	s_waitcnt lgkmcnt(0)
	v_mfma_f32_16x16x32_bf16 v[14:17], v[14:17], v[66:69], v[22:25]
	s_nop 2
	ds_read_b128 v[22:25], v137 offset:896
	v_mfma_f32_16x16x32_bf16 v[18:21], v[18:21], v[66:69], v[26:29]
	s_waitcnt vmcnt(3) lgkmcnt(0)
	v_mfma_f32_16x16x32_bf16 v[26:29], v[6:9], v[22:25], v[38:41]
	s_waitcnt vmcnt(2)
	v_mfma_f32_16x16x32_bf16 v[22:25], v[10:13], v[22:25], v[34:37]
	s_nop 2
	ds_read_b128 v[34:37], v137 offset:17536
	s_waitcnt lgkmcnt(0)
	v_mfma_f32_16x16x32_bf16 v[38:41], v[6:9], v[34:37], v[46:49]
	v_mfma_f32_16x16x32_bf16 v[34:37], v[10:13], v[34:37], v[42:45]
	s_nop 2
	ds_read_b128 v[42:45], v137 offset:34176
	s_waitcnt lgkmcnt(0)
	v_mfma_f32_16x16x32_bf16 v[46:49], v[6:9], v[42:45], v[54:57]
	v_mfma_f32_16x16x32_bf16 v[50:53], v[10:13], v[42:45], v[50:53]
	ds_read_b128 v[42:45], v137 offset:50816
	s_waitcnt lgkmcnt(0)
	v_mfma_f32_16x16x32_bf16 v[54:57], v[6:9], v[42:45], v[62:65]
	v_mfma_f32_16x16x32_bf16 v[58:61], v[10:13], v[42:45], v[58:61]
	ds_read_b128 v[42:45], v147 offset:896
	s_waitcnt lgkmcnt(0)
	v_mfma_f32_16x16x32_bf16 v[62:65], v[6:9], v[42:45], v[14:17]
	ds_read_b128 v[6:9], v137 offset:960
	v_mfma_f32_16x16x32_bf16 v[66:69], v[10:13], v[42:45], v[18:21]
	s_waitcnt vmcnt(1) lgkmcnt(0)
	v_mfma_f32_16x16x32_bf16 v[42:45], v[2:5], v[6:9], v[26:29]
	s_waitcnt vmcnt(0)
	v_mfma_f32_16x16x32_bf16 v[18:21], v[30:33], v[6:9], v[22:25]
	ds_read_b128 v[6:9], v137 offset:17600
	s_waitcnt lgkmcnt(0)
	v_mfma_f32_16x16x32_bf16 v[38:41], v[2:5], v[6:9], v[38:41]
	v_mfma_f32_16x16x32_bf16 v[14:17], v[30:33], v[6:9], v[34:37]
	ds_read_b128 v[6:9], v137 offset:34240
	s_waitcnt lgkmcnt(0)
	v_mfma_f32_16x16x32_bf16 v[34:37], v[2:5], v[6:9], v[46:49]
	s_nop 2
	ds_read_b128 v[46:49], v147 offset:960
	v_mfma_f32_16x16x32_bf16 v[10:13], v[30:33], v[6:9], v[50:53]
	ds_read_b128 v[6:9], v137 offset:50880
	s_waitcnt lgkmcnt(0)
	v_mfma_f32_16x16x32_bf16 v[26:29], v[2:5], v[6:9], v[54:57]
	v_mfma_f32_16x16x32_bf16 v[22:25], v[2:5], v[46:49], v[62:65]
	v_mfma_f32_16x16x32_bf16 v[2:5], v[30:33], v[46:49], v[66:69]
	v_or_b32_e32 v48, s4, v141
	v_ashrrev_i32_e32 v49, 31, v48
	v_lshl_add_u64 v[46:47], v[48:49], 2, s[0:1]
	v_mfma_f32_16x16x32_bf16 v[6:9], v[30:33], v[6:9], v[58:61]
	global_load_dwordx4 v[30:33], v[46:47], off
	v_lshl_add_u32 v54, v48, 1, 0
	v_add_u32_e32 v50, v54, v140
	ds_read_b64 v[50:51], v50
	s_waitcnt lgkmcnt(0)
	v_lshlrev_b32_e32 v52, 16, v50
	v_and_b32_e32 v53, 0xffff0000, v50
	v_lshlrev_b32_e32 v50, 16, v51
	v_and_b32_e32 v51, 0xffff0000, v51
	s_waitcnt vmcnt(0)
; #define LAS __attribute__((address_space(3)))
; __device__ __forceinline__ unsigned pk2(float lo, float hi) { const f32x2cv v = {lo, hi}; return __builtin_bit_cast(unsigned, __builtin_convertvector(v, bf16x2cv)); }
; __device__ __forceinline__ float sigmoidf_(float x) { return __builtin_amdgcn_rcpf(1.0f + __expf(-x)); }
; __device__ __forceinline__ void glu_item(Frame& F, const Args& AR, int l, int item) {
;     ...
; #pragma unroll
;     for (int n = 0; n < 2; ++n) { const int col = colw + n * 16 + 4 * fq; const f32x4 bias = *(const f32x4*)(AR.in[I_GLUB] + l * 512 + col);
; #pragma unroll
;         for (int m = 0; m < MT; ++m) { const int row = m * 16 + fr;
;             if (row < NROW) { const v2u yw = *(const LAS v2u*)(at + row * LDA + col * 2); const f32x4 z = acc[m][n] + bias;
;                 const float o0 = bflo(yw.x) * sigmoidf_(z.x), o1 = bfhi(yw.x) * sigmoidf_(z.y), o2 = bflo(yw.y) * sigmoidf_(z.z), o3 = bfhi(yw.y) * sigmoidf_(z.w);
;                 v2u o; o.x = pk2(o0, o1); o.y = pk2(o2, o3); *(v2u*)(CAT + (size_t)(row0 + row) * DM + 512 + col) = o; } } }
	v_pk_add_f32 v[42:43], v[42:43], v[30:31]
	v_pk_add_f32 v[44:45], v[44:45], v[32:33]
	v_mul_f32_e32 v42, 0xbfb8aa3b, v42
	v_mul_f32_e32 v43, 0xbfb8aa3b, v43
	v_exp_f32_e32 v42, v42
	v_exp_f32_e32 v43, v43
	v_mul_f32_e32 v44, 0xbfb8aa3b, v44
	v_mul_f32_e32 v45, 0xbfb8aa3b, v45
	v_exp_f32_e32 v44, v44
	v_exp_f32_e32 v45, v45
	v_add_f32_e32 v42, 1.0, v42
	v_add_f32_e32 v43, 1.0, v43
	v_rcp_f32_e32 v42, v42
	v_rcp_f32_e32 v43, v43
	v_add_f32_e32 v44, 1.0, v44
	v_add_f32_e32 v45, 1.0, v45
	v_rcp_f32_e32 v44, v44
	v_rcp_f32_e32 v45, v45
	v_pk_mul_f32 v[42:43], v[42:43], v[52:53]
	v_pk_add_f32 v[38:39], v[38:39], v[30:31]
	v_pk_add_f32 v[40:41], v[40:41], v[32:33]
	v_pk_mul_f32 v[44:45], v[44:45], v[50:51]
	v_cvt_pk_bf16_f32 v50, v42, v43
	v_add_u32_e32 v42, s5, v138
	v_ashrrev_i32_e32 v43, 31, v42
	v_lshlrev_b64 v[42:43], 12, v[42:43]
	v_lshl_add_u64 v[42:43], s[90:91], 0, v[42:43]
	v_mul_f32_e32 v38, 0xbfb8aa3b, v38
	v_mul_f32_e32 v39, 0xbfb8aa3b, v39
	v_cvt_pk_bf16_f32 v51, v44, v45
	v_lshl_add_u64 v[42:43], v[42:43], 0, s[18:19]
	v_lshlrev_b64 v[44:45], 1, v[48:49]
	v_exp_f32_e32 v38, v38
	v_exp_f32_e32 v39, v39
	v_mul_f32_e32 v40, 0xbfb8aa3b, v40
	v_mul_f32_e32 v41, 0xbfb8aa3b, v41
	v_lshl_add_u64 v[52:53], v[42:43], 0, v[44:45]
	v_exp_f32_e32 v40, v40
	v_exp_f32_e32 v41, v41
	global_store_dwordx2 v[52:53], v[50:51], off
	v_add_u32_e32 v50, v54, v143
	ds_read_b64 v[52:53], v50
	v_add_f32_e32 v38, 1.0, v38
	v_add_f32_e32 v39, 1.0, v39
	v_rcp_f32_e32 v38, v38
	v_rcp_f32_e32 v39, v39
	v_add_f32_e32 v40, 1.0, v40
	v_add_f32_e32 v41, 1.0, v41
	v_rcp_f32_e32 v40, v40
	v_rcp_f32_e32 v41, v41
	s_waitcnt lgkmcnt(0)
	v_lshlrev_b32_e32 v54, 16, v52
	v_and_b32_e32 v55, 0xffff0000, v52
	v_pk_mul_f32 v[38:39], v[38:39], v[54:55]
	v_lshlrev_b32_e32 v52, 16, v53
	v_and_b32_e32 v53, 0xffff0000, v53
	v_pk_mul_f32 v[40:41], v[40:41], v[52:53]
	v_cvt_pk_bf16_f32 v52, v38, v39
	v_add_u32_e32 v38, s5, v142
	v_ashrrev_i32_e32 v39, 31, v38
	v_pk_add_f32 v[34:35], v[34:35], v[30:31]
	v_lshlrev_b64 v[38:39], 12, v[38:39]
	v_pk_add_f32 v[36:37], v[36:37], v[32:33]
	v_mul_f32_e32 v34, 0xbfb8aa3b, v34
	v_mul_f32_e32 v35, 0xbfb8aa3b, v35
	v_lshl_add_u64 v[38:39], s[90:91], 0, v[38:39]
	v_exp_f32_e32 v34, v34
	v_exp_f32_e32 v35, v35
	v_mul_f32_e32 v36, 0xbfb8aa3b, v36
	v_mul_f32_e32 v37, 0xbfb8aa3b, v37
	v_lshl_add_u64 v[38:39], v[38:39], 0, s[18:19]
	v_exp_f32_e32 v36, v36
	v_exp_f32_e32 v37, v37
	v_cvt_pk_bf16_f32 v53, v40, v41
	v_lshl_add_u64 v[40:41], v[38:39], 0, v[44:45]
	global_store_dwordx2 v[40:41], v[52:53], off
	ds_read_b64 v[40:41], v50 offset:16640
	v_add_f32_e32 v34, 1.0, v34
	v_add_f32_e32 v35, 1.0, v35
	v_rcp_f32_e32 v34, v34
	v_rcp_f32_e32 v35, v35
	v_add_f32_e32 v36, 1.0, v36
	v_add_f32_e32 v37, 1.0, v37
	v_rcp_f32_e32 v36, v36
	v_rcp_f32_e32 v37, v37
	s_waitcnt lgkmcnt(0)
	v_lshlrev_b32_e32 v52, 16, v40
	v_and_b32_e32 v53, 0xffff0000, v40
	v_pk_mul_f32 v[34:35], v[34:35], v[52:53]
	v_lshlrev_b32_e32 v40, 16, v41
	v_and_b32_e32 v41, 0xffff0000, v41
	v_pk_mul_f32 v[36:37], v[36:37], v[40:41]
	v_cvt_pk_bf16_f32 v40, v34, v35
	v_add_u32_e32 v34, s5, v144
	v_ashrrev_i32_e32 v35, 31, v34
	v_pk_add_f32 v[28:29], v[28:29], v[32:33]
	v_pk_add_f32 v[26:27], v[26:27], v[30:31]
	v_lshlrev_b64 v[34:35], 12, v[34:35]
	v_mul_f32_e32 v26, 0xbfb8aa3b, v26
	v_mul_f32_e32 v27, 0xbfb8aa3b, v27
	v_mul_f32_e32 v28, 0xbfb8aa3b, v28
	v_mul_f32_e32 v29, 0xbfb8aa3b, v29
	v_lshl_add_u64 v[34:35], s[90:91], 0, v[34:35]
	v_exp_f32_e32 v26, v26
	v_exp_f32_e32 v27, v27
	v_exp_f32_e32 v28, v28
	v_exp_f32_e32 v29, v29
	v_lshl_add_u64 v[34:35], v[34:35], 0, s[18:19]
	v_cvt_pk_bf16_f32 v41, v36, v37
	v_lshl_add_u64 v[36:37], v[34:35], 0, v[44:45]
	global_store_dwordx2 v[36:37], v[40:41], off
	ds_read_b64 v[36:37], v50 offset:33280
	v_add_f32_e32 v26, 1.0, v26
	v_add_f32_e32 v27, 1.0, v27
	v_add_f32_e32 v28, 1.0, v28
	v_add_f32_e32 v29, 1.0, v29
	v_rcp_f32_e32 v26, v26
	v_rcp_f32_e32 v27, v27
	v_rcp_f32_e32 v28, v28
	v_rcp_f32_e32 v29, v29
	s_waitcnt lgkmcnt(0)
	v_lshlrev_b32_e32 v40, 16, v36
	v_and_b32_e32 v41, 0xffff0000, v36
	v_lshlrev_b32_e32 v36, 16, v37
	v_and_b32_e32 v37, 0xffff0000, v37
	v_pk_mul_f32 v[26:27], v[26:27], v[40:41]
	v_pk_mul_f32 v[28:29], v[28:29], v[36:37]
	v_cvt_pk_bf16_f32 v26, v26, v27
	v_cvt_pk_bf16_f32 v27, v28, v29
	v_add_u32_e32 v28, s5, v145
	v_ashrrev_i32_e32 v29, 31, v28
	v_lshlrev_b64 v[28:29], 12, v[28:29]
	v_lshl_add_u64 v[28:29], s[90:91], 0, v[28:29]
	v_lshl_add_u64 v[28:29], v[28:29], 0, s[18:19]
	v_lshl_add_u64 v[36:37], v[28:29], 0, v[44:45]
	global_store_dwordx2 v[36:37], v[26:27], off
	v_add_u32_e32 v26, s5, v146
	v_ashrrev_i32_e32 v27, 31, v26
	s_and_saveexec_b64 s[4:5], s[40:41]
	s_cbranch_execz .LBB0_1681
	v_pk_add_f32 v[22:23], v[22:23], v[30:31]
	ds_read_b64 v[36:37], v50 offset:49920
	v_mul_f32_e32 v22, 0xbfb8aa3b, v22
	v_exp_f32_e32 v30, v22
	v_mul_f32_e32 v22, 0xbfb8aa3b, v23
	v_exp_f32_e32 v31, v22
	v_pk_add_f32 v[22:23], v[24:25], v[32:33]
	v_add_f32_e32 v24, 1.0, v30
	v_mul_f32_e32 v22, 0xbfb8aa3b, v22
	v_mul_f32_e32 v23, 0xbfb8aa3b, v23
	v_exp_f32_e32 v22, v22
	v_exp_f32_e32 v23, v23
	v_add_f32_e32 v25, 1.0, v31
	v_rcp_f32_e32 v24, v24
	v_rcp_f32_e32 v25, v25
	v_add_f32_e32 v22, 1.0, v22
	v_add_f32_e32 v23, 1.0, v23
	v_rcp_f32_e32 v22, v22
	v_rcp_f32_e32 v23, v23
	s_waitcnt lgkmcnt(0)
	v_lshlrev_b32_e32 v30, 16, v36
	v_and_b32_e32 v31, 0xffff0000, v36
	v_pk_mul_f32 v[24:25], v[24:25], v[30:31]
	v_lshlrev_b32_e32 v30, 16, v37
	v_and_b32_e32 v31, 0xffff0000, v37
	v_pk_mul_f32 v[22:23], v[22:23], v[30:31]
	v_cvt_pk_bf16_f32 v24, v24, v25
	v_cvt_pk_bf16_f32 v25, v22, v23
	v_lshlrev_b64 v[22:23], 12, v[26:27]
	v_lshl_add_u64 v[22:23], s[90:91], 0, v[22:23]
	v_lshl_add_u64 v[22:23], v[48:49], 1, v[22:23]
	v_add_co_u32_e32 v22, vcc, 0x3c500000, v22
	s_nop 1
	v_addc_co_u32_e32 v23, vcc, 0, v23, vcc
	global_store_dwordx2 v[22:23], v[24:25], off offset:1024
